# v24 plus counted lgkmcnt waits in the second-half QK^T phase
# speedup vs baseline: 1.0107x; 1.0000x over previous
; #define SBAR() __builtin_amdgcn_sched_barrier(0)
; __device__ __forceinline__ void qkt(f32x16& p0, f32x16& p1, const bf16_t* Ks, const bf16x8* qr, int r32, int hi) {
;   p0 = f32x16{}; p1 = f32x16{};
; #pragma unroll
;   for (int d0 = 0; d0 < 8; ++d0) { int cb = (d0 * 16 + hi * 8) * 2;
;     bf16x8 b0 = *reinterpret_cast<const bf16x8*>((const char*)Ks + KSWZ(r32, cb));
;     bf16x8 b1 = *reinterpret_cast<const bf16x8*>((const char*)Ks + KSWZ(32 + r32, cb));
;     p0 = __builtin_amdgcn_mfma_f32_32x32x16_bf16(b0, qr[d0], p0, 0, 0, 0);
;     p1 = __builtin_amdgcn_mfma_f32_32x32x16_bf16(b1, qr[d0], p1, 0, 0, 0); }
; __device__ __forceinline__ void attn_body(const bf16_t* __restrict__ Qb, const bf16_t* __restrict__ Kh, const bf16_t* __restrict__ Vh,
;                                           bf16_t* __restrict__ Ob, const bf16_t* __restrict__ AGb, int seq, char* lds) {
;     ...
;     SBAR(); qkt(pA0, pA1, K_lds, qr, r32, hi);
;     finishSM(pB0, pB1, alB, l_reg, pa0, pa1, pa2, pa3); SBAR();
.LBB0_203:
	v_cndmask_b32_e64 v218, v162, v170, s[0:1]
	v_mul_f32_e32 v219, 0xbe0293ee, v218
	v_fmamk_f32 v80, v80, 0x3e0293ee, v219
	v_fmamk_f32 v81, v81, 0x3e0293ee, v219
	v_fmamk_f32 v82, v82, 0x3e0293ee, v219
	v_fmamk_f32 v83, v83, 0x3e0293ee, v219
	v_fmamk_f32 v84, v84, 0x3e0293ee, v219
	v_fmamk_f32 v85, v85, 0x3e0293ee, v219
	v_fmamk_f32 v86, v86, 0x3e0293ee, v219
	v_fmamk_f32 v87, v87, 0x3e0293ee, v219
	v_fmamk_f32 v88, v88, 0x3e0293ee, v219
	v_fmamk_f32 v89, v89, 0x3e0293ee, v219
	v_fmamk_f32 v90, v90, 0x3e0293ee, v219
	v_fmamk_f32 v91, v91, 0x3e0293ee, v219
	v_fmamk_f32 v92, v92, 0x3e0293ee, v219
	v_fmamk_f32 v93, v93, 0x3e0293ee, v219
	v_fmamk_f32 v94, v94, 0x3e0293ee, v219
	v_fmamk_f32 v95, v95, 0x3e0293ee, v219
	v_exp_f32_e32 v162, v80
	v_exp_f32_e32 v177, v81
	v_exp_f32_e32 v163, v82
	v_exp_f32_e32 v176, v83
	v_exp_f32_e32 v164, v84
	v_exp_f32_e32 v175, v85
	v_exp_f32_e32 v165, v86
	v_exp_f32_e32 v174, v87
	v_exp_f32_e32 v166, v88
	v_exp_f32_e32 v173, v89
	v_exp_f32_e32 v167, v90
	v_exp_f32_e32 v172, v91
	v_exp_f32_e32 v168, v92
	v_exp_f32_e32 v171, v93
	v_exp_f32_e32 v169, v94
	v_exp_f32_e32 v170, v95
	v_fmamk_f32 v228, v64, 0x3e0293ee, v219
	v_fmamk_f32 v229, v65, 0x3e0293ee, v219
	v_fmamk_f32 v230, v66, 0x3e0293ee, v219
	v_fmamk_f32 v231, v67, 0x3e0293ee, v219
	v_fmamk_f32 v232, v68, 0x3e0293ee, v219
	v_fmamk_f32 v221, v69, 0x3e0293ee, v219
	v_fmamk_f32 v222, v70, 0x3e0293ee, v219
	v_fmamk_f32 v223, v71, 0x3e0293ee, v219
	v_fmamk_f32 v224, v72, 0x3e0293ee, v219
	v_fmamk_f32 v225, v73, 0x3e0293ee, v219
	v_fmamk_f32 v226, v74, 0x3e0293ee, v219
	v_fmamk_f32 v227, v75, 0x3e0293ee, v219
	v_fmamk_f32 v220, v76, 0x3e0293ee, v219
	v_fmamk_f32 v233, v77, 0x3e0293ee, v219
	v_fmamk_f32 v234, v78, 0x3e0293ee, v219
	v_fmac_f32_e32 v219, 0x3e0293ee, v79
	s_waitcnt lgkmcnt(0)
	s_barrier
	ds_read_b128 v[64:67], v206 offset:32768
	ds_read_b128 v[68:71], v206 offset:40960
	ds_read_b128 v[236:239], v211 offset:32768
	ds_read_b128 v[240:243], v211 offset:40960
	v_exp_f32_e32 v228, v228
	v_exp_f32_e32 v229, v229
	s_waitcnt lgkmcnt(3)
	v_mfma_f32_32x32x16_bf16 v[80:95], v[64:67], v[118:121], 0
	v_exp_f32_e32 v230, v230
	v_exp_f32_e32 v231, v231
	v_exp_f32_e32 v232, v232
	v_exp_f32_e32 v221, v221
	v_exp_f32_e32 v222, v222
	v_exp_f32_e32 v223, v223
	v_exp_f32_e32 v224, v224
	s_waitcnt lgkmcnt(2)
	v_mfma_f32_32x32x16_bf16 v[64:79], v[68:71], v[118:121], 0
	v_exp_f32_e32 v225, v225
	v_exp_f32_e32 v226, v226
	v_exp_f32_e32 v227, v227
	v_exp_f32_e32 v235, v220
	v_exp_f32_e32 v233, v233
	v_exp_f32_e32 v234, v234
	s_waitcnt lgkmcnt(1)
	v_mfma_f32_32x32x16_bf16 v[80:95], v[236:239], v[114:117], v[80:95]
	s_waitcnt lgkmcnt(0)
	v_mfma_f32_32x32x16_bf16 v[64:79], v[240:243], v[114:117], v[64:79]
	ds_read_b128 v[236:239], v210 offset:32768
	ds_read_b128 v[240:243], v210 offset:40960
	s_waitcnt lgkmcnt(1)
	v_mfma_f32_32x32x16_bf16 v[80:95], v[236:239], v[126:129], v[80:95]
	s_waitcnt lgkmcnt(0)
	v_mfma_f32_32x32x16_bf16 v[64:79], v[240:243], v[126:129], v[64:79]
	ds_read_b128 v[236:239], v209 offset:32768
	ds_read_b128 v[240:243], v209 offset:40960
	s_waitcnt lgkmcnt(1)
	v_mfma_f32_32x32x16_bf16 v[80:95], v[236:239], v[122:125], v[80:95]
	s_waitcnt lgkmcnt(0)
	v_mfma_f32_32x32x16_bf16 v[64:79], v[240:243], v[122:125], v[64:79]
	ds_read_b128 v[236:239], v208 offset:32768
	ds_read_b128 v[240:243], v208 offset:40960
	s_waitcnt lgkmcnt(1)
	v_mfma_f32_32x32x16_bf16 v[80:95], v[236:239], v[110:113], v[80:95]
	s_waitcnt lgkmcnt(0)
	v_mfma_f32_32x32x16_bf16 v[64:79], v[240:243], v[110:113], v[64:79]
	ds_read_b128 v[236:239], v207 offset:32768
	ds_read_b128 v[240:243], v207 offset:40960
	s_waitcnt lgkmcnt(1)
	v_mfma_f32_32x32x16_bf16 v[80:95], v[236:239], v[106:109], v[80:95]
	s_waitcnt lgkmcnt(0)
	v_mfma_f32_32x32x16_bf16 v[64:79], v[240:243], v[106:109], v[64:79]
	ds_read_b128 v[236:239], v213 offset:32768
	ds_read_b128 v[240:243], v213 offset:40960
	s_waitcnt lgkmcnt(1)
	v_mfma_f32_32x32x16_bf16 v[80:95], v[236:239], v[102:105], v[80:95]
	s_waitcnt lgkmcnt(0)
	v_mfma_f32_32x32x16_bf16 v[64:79], v[240:243], v[102:105], v[64:79]
	ds_read_b128 v[236:239], v212 offset:32768
	ds_read_b128 v[240:243], v212 offset:40960
	s_waitcnt lgkmcnt(1)
	v_mfma_f32_32x32x16_bf16 v[80:95], v[236:239], v[98:101], v[80:95]
	v_exp_f32_e32 v236, v219
	v_add_f32_e32 v219, 0, v162
	v_add_f32_e32 v219, v177, v219
	v_add_f32_e32 v219, v163, v219
	v_add_f32_e32 v219, v176, v219
	v_add_f32_e32 v219, v164, v219
	v_add_f32_e32 v219, v175, v219
	v_add_f32_e32 v219, v165, v219
	v_add_f32_e32 v219, v174, v219
	v_add_f32_e32 v219, v166, v219
	v_add_f32_e32 v219, v173, v219
	v_add_f32_e32 v219, v167, v219
	v_add_f32_e32 v219, v172, v219
	v_add_f32_e32 v219, v168, v219
	v_add_f32_e32 v219, v171, v219
	v_add_f32_e32 v219, v169, v219
	v_add_f32_e32 v219, v170, v219
	v_add_f32_e32 v219, v228, v219
	v_add_f32_e32 v219, v229, v219
	v_add_f32_e32 v219, v230, v219
	v_add_f32_e32 v219, v231, v219
	v_add_f32_e32 v219, v232, v219
	v_add_f32_e32 v219, v221, v219
	v_add_f32_e32 v219, v222, v219
	v_add_f32_e32 v219, v223, v219
	v_add_f32_e32 v219, v224, v219
	v_add_f32_e32 v219, v225, v219
	s_waitcnt lgkmcnt(0)
	v_mfma_f32_32x32x16_bf16 v[64:79], v[240:243], v[98:101], v[64:79]
	s_cmp_ge_u32 s30, s29
	s_cselect_b64 s[22:23], -1, 0
	s_and_b64 vcc, exec, s[22:23]
	s_cbranch_vccnz .Lap_skipaddr
	v_add_co_u32_e32 v130, vcc, 0x48888000, v188
	s_nop 1
	v_addc_co_u32_e32 v131, vcc, 0, v189, vcc
	v_add_co_u32_e32 v134, vcc, 0x48888000, v186
	s_nop 1
	v_addc_co_u32_e32 v135, vcc, 0, v187, vcc
	v_add_co_u32_e32 v138, vcc, 0x48048000, v188
	s_nop 1
	v_addc_co_u32_e32 v139, vcc, 0, v189, vcc
	v_add_co_u32_e32 v142, vcc, 0x48048000, v186
	s_nop 1
	v_addc_co_u32_e32 v143, vcc, 0, v187, vcc
